# LayerNorm 1/2 phases: waves 4-7 start ~4 us later (one s_sleep 127) so their load burst overlaps the other half's compute/store (de-synchronised bursts)
# speedup vs baseline: 1.0043x; 1.0043x over previous
.LBB0_1219:
	s_cmp_le_i32 s86, s40
	s_cselect_b64 s[0:1], -1, 0
	s_and_b64 s[4:5], s[0:1], s[36:37]
	s_andn2_b64 vcc, exec, s[4:5]
	s_cbranch_vccnz .LBB0_1239
	s_bitcmp1_b32 s88, 8
	s_cbranch_scc0 .Lln_stag_1
	s_sleep 127
.Lln_stag_1:
	v_mbcnt_lo_u32_b32 v0, -1, 0
	v_mbcnt_hi_u32_b32 v0, -1, v0
	s_mov_b32 s6, s74
	v_add_u32_e32 v0, s88, v0
	s_mov_b32 s10, s73
	v_mov_b32_e32 v1, s75
	ds_read_b64 v[2:3], v1
	v_readlane_b32 s4, v254, 12
	v_readfirstlane_b32 s12, v0
	s_ashr_i32 s12, s12, 3
	v_mov_b32_e32 v1, s4
	v_readlane_b32 s4, v254, 18
	s_waitcnt lgkmcnt(0)
	v_readfirstlane_b32 s9, v3
	v_readfirstlane_b32 s8, v2
	ds_read_b64 v[2:3], v1
	v_mov_b32_e32 v1, s4
	v_readlane_b32 s4, v254, 19
	ds_read_b64 v[4:5], v1
	s_lshl_b32 s10, s10, 6
	v_mov_b32_e32 v1, s4
	ds_read_b64 v[6:7], v1
	s_and_b32 s12, s12, -8
	s_add_i32 s10, s10, s12
	s_waitcnt lgkmcnt(0)
	v_readfirstlane_b32 s7, v3
	v_readfirstlane_b32 s20, v2
	v_readfirstlane_b32 s4, v5
	v_readfirstlane_b32 s5, v4
	v_readfirstlane_b32 s11, v7
	s_cmpk_gt_i32 s10, 0x7fff
	v_readfirstlane_b32 s12, v6
	s_cbranch_scc1 .LBB0_1239
	v_readlane_b32 s48, v254, 32
	v_readlane_b32 s49, v254, 33
	s_mov_b32 s17, s49
	s_lshl_b32 s16, s77, 10
	s_mov_b32 s13, s49
	v_readlane_b32 s50, v254, 34
	v_readlane_b32 s51, v254, 35
	v_readlane_b32 s52, v254, 36
	v_readlane_b32 s53, v254, 37
	v_readlane_b32 s54, v254, 38
	v_readlane_b32 s55, v254, 39
	v_readlane_b32 s56, v254, 40
	v_readlane_b32 s57, v254, 41
	v_readlane_b32 s58, v254, 42
	v_readlane_b32 s59, v254, 43
	v_readlane_b32 s60, v254, 44
	v_readlane_b32 s61, v254, 45
	v_readlane_b32 s62, v254, 46
	v_readlane_b32 s63, v254, 47
	v_writelane_b32 v254, s12, 32
	v_and_b32_e32 v0, 63, v0
	v_lshlrev_b32_e32 v232, 4, v0
	v_writelane_b32 v254, s13, 33
	v_writelane_b32 v254, s14, 34
	v_writelane_b32 v254, s15, 35
	v_writelane_b32 v254, s16, 36
	v_writelane_b32 v254, s17, 37
	v_writelane_b32 v254, s18, 38
	v_writelane_b32 v254, s19, 39
	v_writelane_b32 v254, s20, 40
	v_writelane_b32 v254, s21, 41
	v_writelane_b32 v254, s22, 42
	v_writelane_b32 v254, s23, 43
	v_writelane_b32 v254, s24, 44
	v_writelane_b32 v254, s25, 45
	v_writelane_b32 v254, s26, 46
	v_writelane_b32 v254, s27, 47
	s_lshl_b64 s[14:15], s[16:17], 2
	s_add_u32 s12, s12, s14
	s_addc_u32 s13, s11, s15
	s_add_u32 s14, s5, s14
	s_addc_u32 s15, s4, s15
	v_lshl_add_u64 v[136:137], s[12:13], 0, v[232:233]
	s_lshl_b32 s12, s6, 6
	s_ashr_i32 s11, s10, 31
	s_ashr_i32 s13, s12, 31
	s_lshl_b64 s[18:19], s[10:11], 11
	v_lshl_add_u64 v[134:135], s[14:15], 0, v[232:233]
	s_lshl_b64 s[14:15], s[10:11], 3
	s_lshl_b64 s[16:17], s[12:13], 3
	v_lshl_or_b32 v138, v0, 3, s18
	v_mov_b32_e32 v139, s19
	s_lshl_b64 s[18:19], s[12:13], 11
	s_lshl_b64 s[22:23], s[10:11], 12
	s_add_u32 s6, s20, s22
	s_addc_u32 s7, s7, s23
	v_cmp_eq_u32_e64 s[4:5], 0, v0
	v_lshl_add_u64 v[0:1], s[6:7], 0, v[232:233]
	s_mov_b64 s[6:7], 0x7c00
	v_lshl_add_u64 v[140:141], v[0:1], 0, s[6:7]
	s_lshl_b64 s[20:21], s[12:13], 12
	s_branch .LBB0_1223

.LBB0_1547:
	s_cmp_le_i32 s86, s40
	s_cselect_b64 s[8:9], -1, 0
	s_and_b64 s[0:1], s[8:9], s[36:37]
	s_andn2_b64 vcc, exec, s[0:1]
	s_mov_b32 s28, 0xfffff
	s_movk_i32 s29, 0x7e80
	v_readlane_b32 s30, v254, 23
	s_movk_i32 s31, 0x600
	s_mov_b64 s[34:35], 0x400000
	s_cbranch_vccnz .LBB0_1671
	s_bitcmp1_b32 s88, 8
	s_cbranch_scc0 .Lln_stag_2
	s_sleep 127
.Lln_stag_2:
	v_mbcnt_lo_u32_b32 v0, -1, 0
	v_mbcnt_hi_u32_b32 v0, -1, v0
	s_mov_b32 s24, s74
	v_add_u32_e32 v189, s88, v0
	s_mov_b32 s25, s73
	v_mov_b32_e32 v0, s75
	ds_read_b64 v[0:1], v0
	v_readfirstlane_b32 s0, v189
	s_ashr_i32 s27, s0, 6
	s_lshl_b32 s0, s25, 3
	v_readlane_b32 s4, v254, 12
	s_add_i32 s26, s0, s27
	s_waitcnt lgkmcnt(0)
	v_readfirstlane_b32 s0, v0
	v_mov_b32_e32 v0, s4
	v_readfirstlane_b32 s1, v1
	ds_read_b64 v[0:1], v0
	v_readlane_b32 s48, v254, 32
	v_readlane_b32 s49, v254, 33
	s_mov_b32 s13, s49
	v_readlane_b32 s4, v254, 14
	s_waitcnt lgkmcnt(0)
	v_readfirstlane_b32 s21, v1
	v_readfirstlane_b32 s20, v0
	v_readlane_b32 s50, v254, 34
	v_readlane_b32 s51, v254, 35
	v_readlane_b32 s52, v254, 36
	v_readlane_b32 s53, v254, 37
	v_readlane_b32 s54, v254, 38
	v_readlane_b32 s55, v254, 39
	v_readlane_b32 s56, v254, 40
	v_readlane_b32 s57, v254, 41
	v_readlane_b32 s58, v254, 42
	v_readlane_b32 s59, v254, 43
	v_readlane_b32 s60, v254, 44
	v_readlane_b32 s61, v254, 45
	v_readlane_b32 s62, v254, 46
	v_readlane_b32 s63, v254, 47
	v_writelane_b32 v254, s12, 32
	v_mov_b32_e32 v0, s4
	ds_read_b64 v[0:1], v0
	v_writelane_b32 v254, s13, 33
	v_writelane_b32 v254, s14, 34
	v_writelane_b32 v254, s15, 35
	v_writelane_b32 v254, s16, 36
	v_writelane_b32 v254, s17, 37
	v_writelane_b32 v254, s18, 38
	v_writelane_b32 v254, s19, 39
	v_writelane_b32 v254, s20, 40
	v_writelane_b32 v254, s21, 41
	v_writelane_b32 v254, s22, 42
	v_writelane_b32 v254, s23, 43
	v_writelane_b32 v254, s24, 44
	s_mov_b32 s5, s49
	s_lshl_b32 s4, s77, 10
	v_writelane_b32 v254, s25, 45
	s_waitcnt lgkmcnt(0)
	v_readfirstlane_b32 s7, v0
	v_writelane_b32 v254, s26, 46
	s_lshl_b64 s[4:5], s[4:5], 2
	v_readfirstlane_b32 s6, v1
	v_writelane_b32 v254, s27, 47
	s_add_u32 s12, s7, s4
	s_addc_u32 s13, s6, s5
	v_readlane_b32 s6, v254, 16
	v_readlane_b32 s10, v254, 58
	v_readlane_b32 s11, v254, 59
	v_mov_b32_e32 v0, s6
	ds_read_b64 v[0:1], v0
	v_and_b32_e32 v191, 63, v189
	s_waitcnt lgkmcnt(0)
	v_readfirstlane_b32 s7, v0
	v_readfirstlane_b32 s6, v1
	s_add_u32 s14, s7, s4
	s_addc_u32 s15, s6, s5
	s_cmpk_lt_i32 s26, 0x1000
	s_cselect_b64 s[4:5], -1, 0
	v_cndmask_b32_e64 v0, 0, 1, s[4:5]
	s_mov_b64 s[6:7], -1
	s_and_b64 vcc, exec, s[10:11]
	v_cmp_ne_u32_e64 s[4:5], 1, v0
	s_cbranch_vccz .LBB0_1555
	s_and_b64 vcc, exec, s[4:5]
	s_cbranch_vccnz .LBB0_1554
	s_lshl_b32 s10, s26, 3
	s_cmp_lg_u64 s[20:21], 0
	s_cselect_b64 s[16:17], -1, 0
	s_ashr_i32 s11, s10, 31
	s_lshl_b32 s18, s24, 6
	s_lshl_b64 s[6:7], s[10:11], 12
	s_add_u32 s6, s20, s6
	v_lshlrev_b32_e32 v232, 4, v191
	s_addc_u32 s7, s21, s7
	v_lshl_add_u64 v[0:1], s[6:7], 0, v[232:233]
	s_mov_b64 s[6:7], 0x7c00
	s_ashr_i32 s19, s18, 31
	v_lshl_add_u64 v[134:135], s[12:13], 0, v[232:233]
	v_lshl_add_u64 v[136:137], s[14:15], 0, v[232:233]
	v_lshl_add_u64 v[138:139], v[0:1], 0, s[6:7]
	s_lshl_b64 s[22:23], s[18:19], 12
	s_branch .LBB0_1552
